# attention QK^T section re-emitted: K/k_pe/q_pe LDS fragment reads double-buffered, softmax-finish VALU spread over the 24 MFMA gaps
# speedup vs baseline: 1.0162x; 1.0062x over previous
; #define MFMA32(a, b, c) __builtin_amdgcn_mfma_f32_32x32x16_bf16((a), (b), (c), 0, 0, 0)
; DI void a_finishSM(f32x16& p0, f32x16& p1, float alpha, float& l_reg, bf16x8& pa0, bf16x8& pa1, bf16x8& pa2, bf16x8& pa3) {
; #pragma unroll
;   for (int r = 0; r < 16; ++r) p1[r] = __builtin_amdgcn_exp2f(p1[r]);
;   float ps = 0;
; #pragma unroll
;   for (int r = 0; r < 16; ++r) ps += p0[r];
; #pragma unroll
;   for (int r = 0; r < 16; ++r) ps += p1[r];
;   { auto rr = __builtin_amdgcn_permlane32_swap(__float_as_uint(ps), __float_as_uint(ps), false, false);
;     ps = __uint_as_float(rr[0]) + __uint_as_float(rr[1]); }
;   l_reg = l_reg * alpha + ps;
;     ...
;   PK4(p0, 0, pa0); PK4(p0, 8, pa1); PK4(p1, 0, pa2); PK4(p1, 8, pa3);
;     ...
; }
; DI void a_qkt(f32x16& p0, f32x16& p1, const char* Ks, const char* Ps, const bf16x8* qr, const char* QP, int r32, int hi) {
;   p0 = f32x16{}; p1 = f32x16{};
; #pragma unroll
;   for (int d0 = 0; d0 < 8; ++d0) { const int cb = (d0 * 16 + hi * 8) * 2;
;     bf16x8 b0 = *reinterpret_cast<const bf16x8*>(Ks + KSWZ(r32, cb));
;     bf16x8 b1 = *reinterpret_cast<const bf16x8*>(Ks + KSWZ(32 + r32, cb));
;     p0 = MFMA32(b0, qr[d0], p0);
;     p1 = MFMA32(b1, qr[d0], p1); }
; #pragma unroll
;   for (int d0 = 0; d0 < 4; ++d0) { const int cb = (d0 * 16 + hi * 8) * 2;
;     bf16x8 b0 = *reinterpret_cast<const bf16x8*>(Ps + PSWZ(r32, cb));
;     bf16x8 b1 = *reinterpret_cast<const bf16x8*>(Ps + PSWZ(32 + r32, cb));
;     const bf16x8 qp = *reinterpret_cast<const bf16x8*>(QP + d0 * 1024);
;     p0 = MFMA32(b0, qp, p0);
;     p1 = MFMA32(b1, qp, p1); }
; }
.LBB0_665:
	s_mov_b32 s8, s4
	s_add_i32 s4, s7, 0
	v_add_u32_e32 v70, s4, v170
	ds_read_b128 v[66:69], v70 offset:16384
	ds_read_b128 v[82:85], v70 offset:24576
	v_add_u32_e32 v166, s4, v172
	ds_read_b128 v[202:205], v166 offset:16384
	ds_read_b128 v[206:209], v166 offset:24576
	s_waitcnt lgkmcnt(3)
	v_mfma_f32_32x32x16_bf16 v[66:81], v[66:69], v[114:117], 0
	v_exp_f32_e32 v185, v130
	v_exp_f32_e32 v186, v131
	s_waitcnt lgkmcnt(2)
	v_mfma_f32_32x32x16_bf16 v[82:97], v[82:85], v[114:117], 0
	v_add_u32_e32 v166, s4, v173
	ds_read_b128 v[214:217], v166 offset:16384
	ds_read_b128 v[218:221], v166 offset:24576
	v_exp_f32_e32 v187, v146
	v_exp_f32_e32 v188, v147
	s_waitcnt lgkmcnt(3)
	v_mfma_f32_32x32x16_bf16 v[66:81], v[202:205], v[118:121], v[66:81]
	v_exp_f32_e32 v189, v132
	v_exp_f32_e32 v190, v133
	s_waitcnt lgkmcnt(2)
	v_mfma_f32_32x32x16_bf16 v[82:97], v[206:209], v[118:121], v[82:97]
	v_add_u32_e32 v166, s4, v174
	ds_read_b128 v[202:205], v166 offset:16384
	ds_read_b128 v[206:209], v166 offset:24576
	v_exp_f32_e32 v191, v148
	v_exp_f32_e32 v192, v149
	s_waitcnt lgkmcnt(3)
	v_mfma_f32_32x32x16_bf16 v[66:81], v[214:217], v[126:129], v[66:81]
	v_exp_f32_e32 v193, v150
	v_add_f32_e32 v201, 0, v240
	v_add_f32_e32 v201, v241, v201
	s_waitcnt lgkmcnt(2)
	v_mfma_f32_32x32x16_bf16 v[82:97], v[218:221], v[126:129], v[82:97]
	v_add_u32_e32 v166, s4, v175
	ds_read_b128 v[214:217], v166 offset:16384
	ds_read_b128 v[218:221], v166 offset:24576
	v_exp_f32_e32 v194, v151
	v_add_f32_e32 v201, v242, v201
	v_add_f32_e32 v201, v243, v201
	s_waitcnt lgkmcnt(3)
	v_mfma_f32_32x32x16_bf16 v[66:81], v[202:205], v[122:125], v[66:81]
	v_exp_f32_e32 v195, v154
	v_add_f32_e32 v201, v244, v201
	v_add_f32_e32 v201, v245, v201
	s_waitcnt lgkmcnt(2)
	v_mfma_f32_32x32x16_bf16 v[82:97], v[206:209], v[122:125], v[82:97]
	v_add_u32_e32 v166, s4, v176
	ds_read_b128 v[202:205], v166 offset:16384
	ds_read_b128 v[206:209], v166 offset:24576
	v_exp_f32_e32 v196, v155
	v_add_f32_e32 v201, v246, v201
	v_add_f32_e32 v201, v247, v201
	s_waitcnt lgkmcnt(3)
	v_mfma_f32_32x32x16_bf16 v[66:81], v[214:217], v[110:113], v[66:81]
	v_exp_f32_e32 v197, v152
	v_add_f32_e32 v201, v248, v201
	v_add_f32_e32 v201, v249, v201
	s_waitcnt lgkmcnt(2)
	v_mfma_f32_32x32x16_bf16 v[82:97], v[218:221], v[110:113], v[82:97]
	v_add_u32_e32 v166, s4, v177
	ds_read_b128 v[214:217], v166 offset:16384
	ds_read_b128 v[218:221], v166 offset:24576
	v_exp_f32_e32 v198, v153
	v_add_f32_e32 v201, v250, v201
	v_add_f32_e32 v201, v251, v201
	s_waitcnt lgkmcnt(3)
	v_mfma_f32_32x32x16_bf16 v[66:81], v[202:205], v[106:109], v[66:81]
	v_exp_f32_e32 v199, v156
	v_add_f32_e32 v201, v252, v201
	v_add_f32_e32 v201, v253, v201
	s_waitcnt lgkmcnt(2)
	v_mfma_f32_32x32x16_bf16 v[82:97], v[206:209], v[106:109], v[82:97]
	v_add_u32_e32 v166, s4, v178
	ds_read_b128 v[202:205], v166 offset:16384
	ds_read_b128 v[206:209], v166 offset:24576
	v_exp_f32_e32 v200, v157
	v_add_f32_e32 v201, v254, v201
	v_add_f32_e32 v201, v255, v201
	s_waitcnt lgkmcnt(3)
	v_mfma_f32_32x32x16_bf16 v[66:81], v[214:217], v[102:105], v[66:81]
	v_add_f32_e32 v201, v185, v201
	v_add_f32_e32 v201, v186, v201
	v_cvt_pk_bf16_f32 v130, v240, v241
	s_waitcnt lgkmcnt(2)
	v_mfma_f32_32x32x16_bf16 v[82:97], v[218:221], v[102:105], v[82:97]
	v_add_u32_e32 v166, s4, v179
	ds_read_b128 v[214:217], v166 offset:32768
	ds_read_b128 v[218:221], v166 offset:36864
	ds_read_b128 v[222:225], v163
	v_add_f32_e32 v201, v187, v201
	v_add_f32_e32 v201, v188, v201
	v_cvt_pk_bf16_f32 v131, v242, v243
	s_waitcnt lgkmcnt(4)
	v_mfma_f32_32x32x16_bf16 v[66:81], v[202:205], v[98:101], v[66:81]
	v_add_f32_e32 v201, v189, v201
	v_add_f32_e32 v201, v190, v201
	v_cvt_pk_bf16_f32 v132, v244, v245
	s_waitcnt lgkmcnt(3)
	v_mfma_f32_32x32x16_bf16 v[82:97], v[206:209], v[98:101], v[82:97]
	v_add_u32_e32 v166, s4, v180
	ds_read_b128 v[202:205], v166 offset:32768
	ds_read_b128 v[206:209], v166 offset:36864
	ds_read_b128 v[210:213], v163 offset:1024
	v_add_f32_e32 v201, v191, v201
	v_add_f32_e32 v201, v192, v201
	v_cvt_pk_bf16_f32 v133, v246, v247
	s_waitcnt lgkmcnt(3)
	v_mfma_f32_32x32x16_bf16 v[66:81], v[214:217], v[222:225], v[66:81]
	v_add_f32_e32 v201, v193, v201
	v_add_f32_e32 v201, v194, v201
	v_cvt_pk_bf16_f32 v154, v248, v249
	v_mfma_f32_32x32x16_bf16 v[82:97], v[218:221], v[222:225], v[82:97]
	v_add_u32_e32 v166, s4, v181
	ds_read_b128 v[214:217], v166 offset:32768
	ds_read_b128 v[218:221], v166 offset:36864
	ds_read_b128 v[222:225], v163 offset:2048
	v_add_f32_e32 v201, v195, v201
	v_add_f32_e32 v201, v196, v201
	v_cvt_pk_bf16_f32 v155, v250, v251
	s_waitcnt lgkmcnt(3)
	v_mfma_f32_32x32x16_bf16 v[66:81], v[202:205], v[210:213], v[66:81]
	v_add_f32_e32 v201, v197, v201
	v_add_f32_e32 v201, v198, v201
	v_cvt_pk_bf16_f32 v156, v252, v253
	v_mfma_f32_32x32x16_bf16 v[82:97], v[206:209], v[210:213], v[82:97]
	v_add_u32_e32 v166, s4, v182
	ds_read_b128 v[202:205], v166 offset:32768
	ds_read_b128 v[206:209], v166 offset:36864
	ds_read_b128 v[210:213], v163 offset:3072
	v_add_f32_e32 v201, v199, v201
	v_add_f32_e32 v150, v200, v201
	v_cvt_pk_bf16_f32 v157, v254, v255
	s_waitcnt lgkmcnt(3)
	v_mfma_f32_32x32x16_bf16 v[66:81], v[214:217], v[222:225], v[66:81]
	v_mov_b32_e32 v151, v150
	v_cvt_pk_bf16_f32 v184, v185, v186
	v_cvt_pk_bf16_f32 v185, v187, v188
	v_permlane32_swap_b32_e32 v130, v132
	v_mfma_f32_32x32x16_bf16 v[82:97], v[218:221], v[222:225], v[82:97]
	v_cvt_pk_bf16_f32 v186, v189, v190
	v_cvt_pk_bf16_f32 v187, v191, v192
	v_permlane32_swap_b32_e32 v150, v151
	v_permlane32_swap_b32_e32 v131, v133
	s_waitcnt lgkmcnt(0)
; DI void pv_sm(f32x16* o, int vb, bf16x8 pa0, bf16x8 pa1, bf16x8 pa2, bf16x8 pa3, f32x16& p0, f32x16& p1, float& m_reg, float& mn, float& alpha) {
;   PV_BLOCK(0)
;   float pm0 = p0[0];
; #pragma unroll
;   for (int r = 1; r < 16; ++r) pm0 = fmaxf(pm0, p0[r]);
;   PV_BLOCK(1)
;   float pmax = pm0;
; #pragma unroll
;   for (int r = 0; r < 16; ++r) pmax = fmaxf(pmax, p1[r]);
;   { auto rr = __builtin_amdgcn_permlane32_swap(__float_as_uint(pmax), __float_as_uint(pmax), false, false);
;     pmax = fmaxf(__uint_as_float(rr[0]), __uint_as_float(rr[1])); }
;   const bool keep = __all(pmax - m_reg <= ATH);
;   mn = keep ? m_reg : fmaxf(m_reg, pmax);
;   alpha = __builtin_amdgcn_exp2f(m_reg - mn);
;   m_reg = mn;
;   PV_BLOCK(2)
; #pragma unroll
;   for (int r = 0; r < 16; ++r) { p0[r] = p0[r] - mn; p1[r] = p1[r] - mn; }
;   PV_BLOCK(3)
; #pragma unroll
;   for (int r = 0; r < 16; ++r) p0[r] = __builtin_amdgcn_exp2f(p0[r]);
; }
	v_mfma_f32_32x32x16_bf16 v[66:81], v[202:205], v[210:213], v[66:81]
	v_cvt_pk_bf16_f32 v188, v193, v194
	v_cvt_pk_bf16_f32 v189, v195, v196
	v_permlane32_swap_b32_e32 v154, v156
	v_mfma_f32_32x32x16_bf16 v[82:97], v[206:209], v[210:213], v[82:97]
	v_cvt_pk_bf16_f32 v190, v197, v198
	v_cvt_pk_bf16_f32 v191, v199, v200
	v_permlane32_swap_b32_e32 v155, v157
	s_nop 0
	v_permlane32_swap_b32_e32 v184, v186
	v_permlane32_swap_b32_e32 v185, v187
	v_permlane32_swap_b32_e32 v188, v190
	v_permlane32_swap_b32_e32 v189, v191
	v_lshl_add_u64 v[146:147], s[84:85], 0, v[142:143]
	v_add_co_u32_e32 v148, vcc, s56, v146
	s_nop 1
	v_addc_co_u32_e32 v149, vcc, 0, v147, vcc
	v_add_co_u32_e32 v152, vcc, s57, v146
	s_nop 1
	v_addc_co_u32_e32 v153, vcc, 0, v147, vcc
	global_load_dwordx4 v[192:195], v[148:149], off offset:256
	global_load_dwordx4 v[196:199], v[148:149], off
	global_load_dwordx4 v[200:203], v[152:153], off offset:256
	global_load_dwordx4 v[204:207], v[152:153], off
	v_lshl_add_u64 v[148:149], s[84:85], 0, v[140:141]
	v_add_co_u32_e32 v152, vcc, s58, v148
	s_nop 1
	v_addc_co_u32_e32 v153, vcc, 0, v149, vcc
	global_load_dwordx4 v[208:211], v[152:153], off
	v_add_u32_e32 v166, s8, v171
	ds_read_b64_tr_b16 v[212:213], v166 offset:0
	ds_read_b64_tr_b16 v[214:215], v166 offset:0x800
	ds_read_b64_tr_b16 v[216:217], v166 offset:0x1000
	ds_read_b64_tr_b16 v[218:219], v166 offset:0x1800
	ds_read_b64_tr_b16 v[220:221], v166 offset:0x2000
	ds_read_b64_tr_b16 v[222:223], v166 offset:0x2800
	ds_read_b64_tr_b16 v[224:225], v166 offset:0x3000
	ds_read_b64_tr_b16 v[226:227], v166 offset:0x3800
	s_waitcnt lgkmcnt(0)
	s_nop 0
	v_mfma_f32_32x32x16_bf16 v[2:17], v[130:133], v[212:215], v[2:17]
	ds_read_b64_tr_b16 v[212:213], v166 offset:0x200
	ds_read_b64_tr_b16 v[214:215], v166 offset:0xa00
	v_max_f32_e32 v152, v67, v67
	v_max_f32_e32 v153, v66, v66
	v_max_f32_e32 v152, v153, v152
	v_max3_f32 v152, v152, v68, v69
	v_max3_f32 v152, v152, v70, v71
	v_mfma_f32_32x32x16_bf16 v[2:17], v[154:157], v[216:219], v[2:17]
	ds_read_b64_tr_b16 v[216:217], v166 offset:0x1200
	ds_read_b64_tr_b16 v[218:219], v166 offset:0x1a00
	v_max3_f32 v152, v152, v72, v73
	v_max3_f32 v152, v152, v74, v75
	v_max3_f32 v152, v152, v76, v77
	v_max3_f32 v152, v152, v78, v79
	v_max3_f32 v152, v152, v80, v81
	v_mfma_f32_32x32x16_bf16 v[2:17], v[184:187], v[220:223], v[2:17]
	ds_read_b64_tr_b16 v[220:221], v166 offset:0x2200
	ds_read_b64_tr_b16 v[222:223], v166 offset:0x2a00
	ds_read_b64_tr_b16 v[228:229], v166 offset:0x3200
	ds_read_b64_tr_b16 v[230:231], v166 offset:0x3a00
	s_waitcnt lgkmcnt(0)
	v_mfma_f32_32x32x16_bf16 v[2:17], v[188:191], v[224:227], v[2:17]
	v_mfma_f32_32x32x16_bf16 v[50:65], v[130:133], v[212:215], v[50:65]
	v_max3_f32 v152, v152, v82, v83
	v_max3_f32 v152, v152, v84, v85
	v_max3_f32 v152, v152, v86, v87
	v_max3_f32 v152, v152, v88, v89
	v_max3_f32 v152, v152, v90, v91
	v_max3_f32 v152, v152, v92, v93
	v_max3_f32 v152, v152, v94, v95
	v_mfma_f32_32x32x16_bf16 v[50:65], v[154:157], v[216:219], v[50:65]
	v_max3_f32 v152, v152, v96, v97
	v_mov_b32_e32 v153, v152
	s_nop 1
	v_permlane32_swap_b32_e32 v152, v153
	v_max_f32_e32 v153, v153, v153
	v_max_f32_e32 v152, v152, v152
	v_max_f32_e32 v152, v152, v153
	v_mfma_f32_32x32x16_bf16 v[50:65], v[184:187], v[220:223], v[50:65]
	ds_read_b64_tr_b16 v[212:213], v166 offset:0x400
	v_sub_f32_e32 v153, v152, v144
	ds_read_b64_tr_b16 v[214:215], v166 offset:0xc00
	v_cmp_ge_f32_e32 vcc, s54, v153
	ds_read_b64_tr_b16 v[216:217], v166 offset:0x1400
	s_cmp_eq_u64 vcc, exec
	v_max_f32_e32 v153, v144, v144
	ds_read_b64_tr_b16 v[218:219], v166 offset:0x1c00
	v_mfma_f32_32x32x16_bf16 v[50:65], v[188:191], v[228:231], v[50:65]
	v_max_f32_e32 v152, v153, v152
	s_cselect_b64 vcc, -1, 0
	ds_read_b64_tr_b16 v[220:221], v166 offset:0x2400
	v_cndmask_b32_e32 v153, v152, v144, vcc
	ds_read_b64_tr_b16 v[222:223], v166 offset:0x2c00
	v_sub_f32_e32 v144, v144, v153
	ds_read_b64_tr_b16 v[224:225], v166 offset:0x3400
	v_exp_f32_e32 v152, v144
	ds_read_b64_tr_b16 v[226:227], v166 offset:0x3c00
	s_waitcnt lgkmcnt(0)
	v_mfma_f32_32x32x16_bf16 v[34:49], v[130:133], v[212:215], v[34:49]
	ds_read_b64_tr_b16 v[212:213], v166 offset:0x600
	ds_read_b64_tr_b16 v[214:215], v166 offset:0xe00
	v_sub_f32_e32 v66, v66, v153
	v_sub_f32_e32 v67, v67, v153
	v_sub_f32_e32 v68, v68, v153
	v_sub_f32_e32 v69, v69, v153
	v_mfma_f32_32x32x16_bf16 v[34:49], v[154:157], v[216:219], v[34:49]
	ds_read_b64_tr_b16 v[216:217], v166 offset:0x1600
	ds_read_b64_tr_b16 v[218:219], v166 offset:0x1e00
	v_sub_f32_e32 v70, v70, v153
	v_sub_f32_e32 v71, v71, v153
	v_exp_f32_e32 v240, v66
	v_exp_f32_e32 v241, v67
	v_mfma_f32_32x32x16_bf16 v[34:49], v[184:187], v[220:223], v[34:49]
	ds_read_b64_tr_b16 v[220:221], v166 offset:0x2600
	ds_read_b64_tr_b16 v[222:223], v166 offset:0x2e00
	ds_read_b64_tr_b16 v[228:229], v166 offset:0x3600
	ds_read_b64_tr_b16 v[230:231], v166 offset:0x3e00
	v_sub_f32_e32 v72, v72, v153
	v_sub_f32_e32 v73, v73, v153
	v_exp_f32_e32 v242, v68
	v_exp_f32_e32 v243, v69
	s_waitcnt lgkmcnt(0)
	v_mfma_f32_32x32x16_bf16 v[34:49], v[188:191], v[224:227], v[34:49]
	v_sub_f32_e32 v74, v74, v153
	v_sub_f32_e32 v75, v75, v153
	v_exp_f32_e32 v244, v70
	v_exp_f32_e32 v245, v71
	v_mfma_f32_32x32x16_bf16 v[18:33], v[130:133], v[212:215], v[18:33]
	v_sub_f32_e32 v76, v76, v153
	v_sub_f32_e32 v77, v77, v153
	v_exp_f32_e32 v246, v72
	v_exp_f32_e32 v247, v73
	s_add_i32 s9, s6, 0
	v_add_u32_e32 v130, s9, v164
	s_waitcnt vmcnt(0)
	s_waitcnt vmcnt(4)
	ds_write_b128 v130, v[192:195]
	v_add_u32_e32 v130, s9, v165
	s_waitcnt vmcnt(2)
	ds_write_b128 v130, v[200:203]
	v_add_u32_e32 v130, s9, v167
	v_mfma_f32_32x32x16_bf16 v[18:33], v[154:157], v[216:219], v[18:33]
	ds_write_b128 v130, v[196:199] offset:16384
	v_add_u32_e32 v130, s9, v168
	s_waitcnt vmcnt(1)
	ds_write_b128 v130, v[204:207] offset:16384
	v_add_u32_e32 v130, s9, v169
	v_cmp_gt_f32_e32 vcc, 1.0, v152
	s_waitcnt vmcnt(0)
	ds_write_b128 v130, v[208:211] offset:32768
	v_sub_f32_e32 v78, v78, v153
	v_sub_f32_e32 v79, v79, v153
	v_exp_f32_e32 v248, v74
	v_exp_f32_e32 v249, v75
	v_mfma_f32_32x32x16_bf16 v[18:33], v[184:187], v[220:223], v[18:33]
	v_sub_f32_e32 v80, v80, v153
	v_sub_f32_e32 v81, v81, v153
	v_exp_f32_e32 v250, v76
	v_exp_f32_e32 v251, v77
	v_mfma_f32_32x32x16_bf16 v[18:33], v[188:191], v[228:231], v[18:33]
	v_exp_f32_e32 v252, v78
	v_exp_f32_e32 v253, v79
	v_exp_f32_e32 v254, v80
	v_exp_f32_e32 v255, v81
	s_cbranch_vccz .LBB0_669
; #define MFMA32(a, b, c) __builtin_amdgcn_mfma_f32_32x32x16_bf16((a), (b), (c), 0, 0, 0)
; DI void a_finishSM(f32x16& p0, f32x16& p1, float alpha, float& l_reg, bf16x8& pa0, bf16x8& pa1, bf16x8& pa2, bf16x8& pa3) {
; #pragma unroll
;   for (int r = 0; r < 16; ++r) p1[r] = __builtin_amdgcn_exp2f(p1[r]);
;   float ps = 0;
; #pragma unroll
;   for (int r = 0; r < 16; ++r) ps += p0[r];
; #pragma unroll
;   for (int r = 0; r < 16; ++r) ps += p1[r];
;   { auto rr = __builtin_amdgcn_permlane32_swap(__float_as_uint(ps), __float_as_uint(ps), false, false);
;     ps = __uint_as_float(rr[0]) + __uint_as_float(rr[1]); }
;   l_reg = l_reg * alpha + ps;
;     ...
;   PK4(p0, 0, pa0); PK4(p0, 8, pa1); PK4(p1, 0, pa2); PK4(p1, 8, pa3);
;     ...
; }
; DI void a_qkt(f32x16& p0, f32x16& p1, const char* Ks, const char* Ps, const bf16x8* qr, const char* QP, int r32, int hi) {
;   p0 = f32x16{}; p1 = f32x16{};
; #pragma unroll
;   for (int d0 = 0; d0 < 8; ++d0) { const int cb = (d0 * 16 + hi * 8) * 2;
;     bf16x8 b0 = *reinterpret_cast<const bf16x8*>(Ks + KSWZ(r32, cb));
;     bf16x8 b1 = *reinterpret_cast<const bf16x8*>(Ks + KSWZ(32 + r32, cb));
;     p0 = MFMA32(b0, qr[d0], p0);
;     p1 = MFMA32(b1, qr[d0], p1); }
; #pragma unroll
;   for (int d0 = 0; d0 < 4; ++d0) { const int cb = (d0 * 16 + hi * 8) * 2;
;     bf16x8 b0 = *reinterpret_cast<const bf16x8*>(Ps + PSWZ(r32, cb));
;     bf16x8 b1 = *reinterpret_cast<const bf16x8*>(Ps + PSWZ(32 + r32, cb));
;     const bf16x8 qp = *reinterpret_cast<const bf16x8*>(QP + d0 * 1024);
;     p0 = MFMA32(b0, qp, p0);
;     p1 = MFMA32(b1, qp, p1); }
; }
	s_and_saveexec_b64 s[4:5], s[2:3]
	ds_write_b32 v161, v152 offset:128
	s_or_b64 exec, exec, s[4:5]
	s_waitcnt lgkmcnt(0)
	v_add_u32_e32 v144, v137, v134
	ds_read_b128 v[130:133], v144 offset:224
	ds_read_b128 v[154:157], v144 offset:192
	ds_read_b128 v[184:187], v144 offset:160
	ds_read_b128 v[188:191], v144 offset:128
	s_waitcnt lgkmcnt(3)
	v_pk_mul_f32 v[14:15], v[14:15], v[130:131]
	s_waitcnt lgkmcnt(2)
	v_pk_mul_f32 v[10:11], v[10:11], v[154:155]
	s_waitcnt lgkmcnt(1)
	v_pk_mul_f32 v[6:7], v[6:7], v[184:185]
	v_pk_mul_f32 v[16:17], v[16:17], v[132:133]
	v_pk_mul_f32 v[12:13], v[12:13], v[156:157]
	v_pk_mul_f32 v[8:9], v[8:9], v[186:187]
	s_waitcnt lgkmcnt(0)
	v_pk_mul_f32 v[4:5], v[4:5], v[190:191]
	v_pk_mul_f32 v[2:3], v[2:3], v[188:189]
	v_pk_mul_f32 v[62:63], v[62:63], v[130:131]
	v_pk_mul_f32 v[58:59], v[58:59], v[154:155]
	v_pk_mul_f32 v[54:55], v[54:55], v[184:185]
	v_pk_mul_f32 v[64:65], v[64:65], v[132:133]
	v_pk_mul_f32 v[60:61], v[60:61], v[156:157]
	v_pk_mul_f32 v[56:57], v[56:57], v[186:187]
	v_pk_mul_f32 v[52:53], v[52:53], v[190:191]
	v_pk_mul_f32 v[50:51], v[50:51], v[188:189]
	v_pk_mul_f32 v[46:47], v[46:47], v[130:131]
	v_pk_mul_f32 v[42:43], v[42:43], v[154:155]
	v_pk_mul_f32 v[38:39], v[38:39], v[184:185]
	v_pk_mul_f32 v[48:49], v[48:49], v[132:133]
	v_pk_mul_f32 v[44:45], v[44:45], v[156:157]
	v_pk_mul_f32 v[40:41], v[40:41], v[186:187]
	v_pk_mul_f32 v[36:37], v[36:37], v[190:191]
	v_pk_mul_f32 v[34:35], v[34:35], v[188:189]
	v_pk_mul_f32 v[30:31], v[30:31], v[130:131]
	v_pk_mul_f32 v[26:27], v[26:27], v[154:155]
	v_pk_mul_f32 v[22:23], v[22:23], v[184:185]
	v_pk_mul_f32 v[32:33], v[32:33], v[132:133]
	v_pk_mul_f32 v[28:29], v[28:29], v[156:157]
	v_pk_mul_f32 v[24:25], v[24:25], v[186:187]
	v_pk_mul_f32 v[20:21], v[20:21], v[190:191]
	v_pk_mul_f32 v[18:19], v[18:19], v[188:189]
.LBB0_669:
	s_waitcnt lgkmcnt(0)
	s_barrier
	v_add_u32_e32 v70, s9, v170
	ds_read_b128 v[66:69], v70 offset:16384
	ds_read_b128 v[70:73], v70 offset:24576
	v_add_u32_e32 v226, s9, v172
	ds_read_b128 v[216:219], v226 offset:16384
	ds_read_b128 v[220:223], v226 offset:24576
	v_sub_f32_e32 v144, v82, v153
	v_sub_f32_e32 v188, v83, v153
	v_sub_f32_e32 v189, v84, v153
	v_sub_f32_e32 v190, v85, v153
	v_sub_f32_e32 v191, v86, v153
	v_sub_f32_e32 v192, v87, v153
	v_sub_f32_e32 v193, v88, v153
	v_sub_f32_e32 v194, v89, v153
	v_sub_f32_e32 v195, v90, v153
	v_sub_f32_e32 v196, v91, v153
	v_sub_f32_e32 v197, v92, v153
	v_sub_f32_e32 v198, v93, v153
	v_sub_f32_e32 v199, v94, v153
	v_sub_f32_e32 v200, v95, v153
	v_sub_f32_e32 v201, v96, v153
	v_sub_f32_e32 v202, v97, v153
	s_waitcnt lgkmcnt(3)
	v_mfma_f32_32x32x16_bf16 v[82:97], v[66:69], v[114:117], 0
	v_exp_f32_e32 v144, v144
	v_exp_f32_e32 v156, v188
	s_waitcnt lgkmcnt(2)
	v_mfma_f32_32x32x16_bf16 v[66:81], v[70:73], v[114:117], 0
	v_add_u32_e32 v226, s9, v173
	ds_read_b128 v[204:207], v226 offset:16384
	ds_read_b128 v[208:211], v226 offset:24576
	v_exp_f32_e32 v157, v189
	v_exp_f32_e32 v184, v190
	s_waitcnt lgkmcnt(3)
	v_mfma_f32_32x32x16_bf16 v[82:97], v[216:219], v[118:121], v[82:97]
	v_exp_f32_e32 v185, v191
	v_exp_f32_e32 v192, v192
	s_waitcnt lgkmcnt(2)
	v_mfma_f32_32x32x16_bf16 v[66:81], v[220:223], v[118:121], v[66:81]
	v_add_u32_e32 v226, s9, v174
	ds_read_b128 v[216:219], v226 offset:16384
	ds_read_b128 v[220:223], v226 offset:24576
	v_exp_f32_e32 v193, v193
	v_exp_f32_e32 v194, v194
	s_waitcnt lgkmcnt(3)
	v_mfma_f32_32x32x16_bf16 v[82:97], v[204:207], v[126:129], v[82:97]
	v_exp_f32_e32 v195, v195
	v_add_f32_e32 v203, 0, v240
	v_add_f32_e32 v203, v241, v203
	s_waitcnt lgkmcnt(2)
	v_mfma_f32_32x32x16_bf16 v[66:81], v[208:211], v[126:129], v[66:81]
	v_add_u32_e32 v226, s9, v175
	ds_read_b128 v[204:207], v226 offset:16384
	ds_read_b128 v[208:211], v226 offset:24576
	v_exp_f32_e32 v196, v196
	v_add_f32_e32 v203, v242, v203
	v_add_f32_e32 v203, v243, v203
	s_waitcnt lgkmcnt(3)
	v_mfma_f32_32x32x16_bf16 v[82:97], v[216:219], v[122:125], v[82:97]
	v_exp_f32_e32 v197, v197
	v_add_f32_e32 v203, v244, v203
	v_add_f32_e32 v203, v245, v203
	s_waitcnt lgkmcnt(2)
	v_mfma_f32_32x32x16_bf16 v[66:81], v[220:223], v[122:125], v[66:81]
	v_add_u32_e32 v226, s9, v176
	ds_read_b128 v[216:219], v226 offset:16384
	ds_read_b128 v[220:223], v226 offset:24576
	v_exp_f32_e32 v198, v198
	v_add_f32_e32 v203, v246, v203
	v_add_f32_e32 v203, v247, v203
	s_waitcnt lgkmcnt(3)
	v_mfma_f32_32x32x16_bf16 v[82:97], v[204:207], v[110:113], v[82:97]
	v_exp_f32_e32 v199, v199
	v_add_f32_e32 v203, v248, v203
	v_add_f32_e32 v203, v249, v203
	s_waitcnt lgkmcnt(2)
	v_mfma_f32_32x32x16_bf16 v[66:81], v[208:211], v[110:113], v[66:81]
	v_add_u32_e32 v226, s9, v177
	ds_read_b128 v[204:207], v226 offset:16384
	ds_read_b128 v[208:211], v226 offset:24576
	v_exp_f32_e32 v200, v200
	v_add_f32_e32 v203, v250, v203
	v_add_f32_e32 v203, v251, v203
	s_waitcnt lgkmcnt(3)
	v_mfma_f32_32x32x16_bf16 v[82:97], v[216:219], v[106:109], v[82:97]
	v_exp_f32_e32 v201, v201
	v_add_f32_e32 v203, v252, v203
	v_add_f32_e32 v203, v253, v203
	s_waitcnt lgkmcnt(2)
	v_mfma_f32_32x32x16_bf16 v[66:81], v[220:223], v[106:109], v[66:81]
	v_add_u32_e32 v226, s9, v178
	ds_read_b128 v[216:219], v226 offset:16384
	ds_read_b128 v[220:223], v226 offset:24576
	v_exp_f32_e32 v202, v202
	v_add_f32_e32 v203, v254, v203
	v_add_f32_e32 v203, v255, v203
	s_waitcnt lgkmcnt(3)
	v_mfma_f32_32x32x16_bf16 v[82:97], v[204:207], v[102:105], v[82:97]
	v_add_f32_e32 v203, v144, v203
	v_add_f32_e32 v203, v156, v203
	v_cvt_pk_bf16_f32 v130, v240, v241
	s_waitcnt lgkmcnt(2)
; #define MFMA32(a, b, c) __builtin_amdgcn_mfma_f32_32x32x16_bf16((a), (b), (c), 0, 0, 0)
; DI void a_qkt(f32x16& p0, f32x16& p1, const char* Ks, const char* Ps, const bf16x8* qr, const char* QP, int r32, int hi) {
;   p0 = f32x16{}; p1 = f32x16{};
; #pragma unroll
;   for (int d0 = 0; d0 < 8; ++d0) { const int cb = (d0 * 16 + hi * 8) * 2;
;     bf16x8 b0 = *reinterpret_cast<const bf16x8*>(Ks + KSWZ(r32, cb));
;     bf16x8 b1 = *reinterpret_cast<const bf16x8*>(Ks + KSWZ(32 + r32, cb));
;     p0 = MFMA32(b0, qr[d0], p0);
;     p1 = MFMA32(b1, qr[d0], p1); }
; #pragma unroll
;   for (int d0 = 0; d0 < 4; ++d0) { const int cb = (d0 * 16 + hi * 8) * 2;
;     bf16x8 b0 = *reinterpret_cast<const bf16x8*>(Ps + PSWZ(r32, cb));
;     bf16x8 b1 = *reinterpret_cast<const bf16x8*>(Ps + PSWZ(32 + r32, cb));
;     const bf16x8 qp = *reinterpret_cast<const bf16x8*>(QP + d0 * 1024);
;     p0 = MFMA32(b0, qp, p0);
;     p1 = MFMA32(b1, qp, p1); }
; }
; DI void pv_sm(f32x16* o, int vb, bf16x8 pa0, bf16x8 pa1, bf16x8 pa2, bf16x8 pa3, f32x16& p0, f32x16& p1, float& m_reg, float& mn, float& alpha) {
;   PV_BLOCK(0)
;   float pm0 = p0[0];
; #pragma unroll
;   for (int r = 1; r < 16; ++r) pm0 = fmaxf(pm0, p0[r]);
;   PV_BLOCK(1)
;   float pmax = pm0;
; #pragma unroll
;   for (int r = 0; r < 16; ++r) pmax = fmaxf(pmax, p1[r]);
	v_mfma_f32_32x32x16_bf16 v[66:81], v[208:211], v[102:105], v[66:81]
	v_add_u32_e32 v226, s9, v179
	ds_read_b128 v[204:207], v226 offset:32768
	ds_read_b128 v[208:211], v226 offset:36864
	ds_read_b128 v[212:215], v163
	v_add_f32_e32 v203, v157, v203
	v_add_f32_e32 v203, v184, v203
	v_cvt_pk_bf16_f32 v131, v242, v243
	s_waitcnt lgkmcnt(4)
	v_mfma_f32_32x32x16_bf16 v[82:97], v[216:219], v[98:101], v[82:97]
	v_add_f32_e32 v203, v185, v203
	v_add_f32_e32 v203, v192, v203
	v_cvt_pk_bf16_f32 v132, v244, v245
	s_waitcnt lgkmcnt(3)
	v_mfma_f32_32x32x16_bf16 v[66:81], v[220:223], v[98:101], v[66:81]
	v_add_u32_e32 v226, s9, v180
	ds_read_b128 v[216:219], v226 offset:32768
	ds_read_b128 v[220:223], v226 offset:36864
	ds_read_b128 v[228:231], v163 offset:1024
	v_add_f32_e32 v203, v193, v203
	v_add_f32_e32 v203, v194, v203
	v_cvt_pk_bf16_f32 v133, v246, v247
	s_waitcnt lgkmcnt(3)
	v_mfma_f32_32x32x16_bf16 v[82:97], v[204:207], v[212:215], v[82:97]
	v_add_f32_e32 v203, v195, v203
	v_add_f32_e32 v203, v196, v203
	v_cvt_pk_bf16_f32 v186, v248, v249
	v_mfma_f32_32x32x16_bf16 v[66:81], v[208:211], v[212:215], v[66:81]
	v_add_u32_e32 v226, s9, v181
	ds_read_b128 v[204:207], v226 offset:32768
	ds_read_b128 v[208:211], v226 offset:36864
	ds_read_b128 v[212:215], v163 offset:2048
	v_add_f32_e32 v203, v197, v203
	v_add_f32_e32 v203, v198, v203
	v_cvt_pk_bf16_f32 v187, v250, v251
	s_waitcnt lgkmcnt(3)
	v_mfma_f32_32x32x16_bf16 v[82:97], v[216:219], v[228:231], v[82:97]
	v_add_f32_e32 v203, v199, v203
	v_add_f32_e32 v203, v200, v203
	v_cvt_pk_bf16_f32 v188, v252, v253
	v_mfma_f32_32x32x16_bf16 v[66:81], v[220:223], v[228:231], v[66:81]
	v_add_u32_e32 v226, s9, v182
	ds_read_b128 v[216:219], v226 offset:32768
	ds_read_b128 v[220:223], v226 offset:36864
	ds_read_b128 v[228:231], v163 offset:3072
	v_add_f32_e32 v203, v201, v203
	v_add_f32_e32 v154, v202, v203
	v_cvt_pk_bf16_f32 v189, v254, v255
	s_waitcnt lgkmcnt(3)
	v_mfma_f32_32x32x16_bf16 v[82:97], v[204:207], v[212:215], v[82:97]
	v_mov_b32_e32 v155, v154
	v_cvt_pk_bf16_f32 v190, v144, v156
	v_cvt_pk_bf16_f32 v191, v157, v184
	v_permlane32_swap_b32_e32 v130, v132
	v_mfma_f32_32x32x16_bf16 v[66:81], v[208:211], v[212:215], v[66:81]
	v_cvt_pk_bf16_f32 v192, v185, v192
	v_cvt_pk_bf16_f32 v193, v193, v194
	v_permlane32_swap_b32_e32 v154, v155
	v_permlane32_swap_b32_e32 v131, v133
	s_waitcnt lgkmcnt(0)
	v_mfma_f32_32x32x16_bf16 v[82:97], v[216:219], v[228:231], v[82:97]
	v_cvt_pk_bf16_f32 v194, v195, v196
	v_cvt_pk_bf16_f32 v195, v197, v198
	v_permlane32_swap_b32_e32 v186, v188
	v_mfma_f32_32x32x16_bf16 v[66:81], v[220:223], v[228:231], v[66:81]
	v_cvt_pk_bf16_f32 v196, v199, v200
	v_cvt_pk_bf16_f32 v197, v201, v202
	v_permlane32_swap_b32_e32 v187, v189
	s_nop 0
	v_permlane32_swap_b32_e32 v190, v192
	v_permlane32_swap_b32_e32 v191, v193
	v_permlane32_swap_b32_e32 v194, v196
	v_permlane32_swap_b32_e32 v195, v197
	v_add_co_u32_e32 v156, vcc, s59, v146
	s_nop 1
	v_addc_co_u32_e32 v157, vcc, 0, v147, vcc
	v_add_co_u32_e32 v146, vcc, s60, v146
	s_nop 1
	v_addc_co_u32_e32 v147, vcc, 0, v147, vcc
	global_load_dwordx4 v[198:201], v[156:157], off offset:256
	global_load_dwordx4 v[202:205], v[156:157], off
	global_load_dwordx4 v[206:209], v[146:147], off offset:256
	global_load_dwordx4 v[210:213], v[146:147], off
	v_add_co_u32_e32 v146, vcc, s61, v148
	s_nop 1
	v_addc_co_u32_e32 v147, vcc, 0, v149, vcc
	global_load_dwordx4 v[146:149], v[146:147], off
	v_add_u32_e32 v156, s7, v171
	ds_read_b64_tr_b16 v[214:215], v156 offset:0
	ds_read_b64_tr_b16 v[216:217], v156 offset:0x800
	ds_read_b64_tr_b16 v[218:219], v156 offset:0x1000
	ds_read_b64_tr_b16 v[220:221], v156 offset:0x1800
	ds_read_b64_tr_b16 v[222:223], v156 offset:0x2000
	ds_read_b64_tr_b16 v[224:225], v156 offset:0x2800
	ds_read_b64_tr_b16 v[226:227], v156 offset:0x3000
	ds_read_b64_tr_b16 v[228:229], v156 offset:0x3800
	s_waitcnt lgkmcnt(0)
	s_nop 0
	v_mfma_f32_32x32x16_bf16 v[2:17], v[130:133], v[214:217], v[2:17]
	ds_read_b64_tr_b16 v[214:215], v156 offset:0x200
	ds_read_b64_tr_b16 v[216:217], v156 offset:0xa00
	v_max_f32_e32 v144, v83, v83
	v_max_f32_e32 v157, v82, v82
	v_max_f32_e32 v144, v157, v144
	v_max3_f32 v144, v144, v84, v85
	v_max3_f32 v144, v144, v86, v87
	v_mfma_f32_32x32x16_bf16 v[2:17], v[186:189], v[218:221], v[2:17]
	ds_read_b64_tr_b16 v[218:219], v156 offset:0x1200
	ds_read_b64_tr_b16 v[220:221], v156 offset:0x1a00
	v_max3_f32 v144, v144, v88, v89
	v_max3_f32 v144, v144, v90, v91
	v_max3_f32 v144, v144, v92, v93
	v_max3_f32 v144, v144, v94, v95
	v_max3_f32 v144, v144, v96, v97
	v_mfma_f32_32x32x16_bf16 v[2:17], v[190:193], v[222:225], v[2:17]
	ds_read_b64_tr_b16 v[222:223], v156 offset:0x2200
	ds_read_b64_tr_b16 v[224:225], v156 offset:0x2a00
	ds_read_b64_tr_b16 v[230:231], v156 offset:0x3200
	ds_read_b64_tr_b16 v[232:233], v156 offset:0x3a00
	s_waitcnt lgkmcnt(0)
; DI void pv_sm(f32x16* o, int vb, bf16x8 pa0, bf16x8 pa1, bf16x8 pa2, bf16x8 pa3, f32x16& p0, f32x16& p1, float& m_reg, float& mn, float& alpha) {
;   PV_BLOCK(0)
;   float pm0 = p0[0];
; #pragma unroll
;   for (int r = 1; r < 16; ++r) pm0 = fmaxf(pm0, p0[r]);
;   PV_BLOCK(1)
;   float pmax = pm0;
; #pragma unroll
;   for (int r = 0; r < 16; ++r) pmax = fmaxf(pmax, p1[r]);
;   { auto rr = __builtin_amdgcn_permlane32_swap(__float_as_uint(pmax), __float_as_uint(pmax), false, false);
;     pmax = fmaxf(__uint_as_float(rr[0]), __uint_as_float(rr[1])); }
;   const bool keep = __all(pmax - m_reg <= ATH);
;   mn = keep ? m_reg : fmaxf(m_reg, pmax);
;   alpha = __builtin_amdgcn_exp2f(m_reg - mn);
;   m_reg = mn;
;   PV_BLOCK(2)
; #pragma unroll
;   for (int r = 0; r < 16; ++r) { p0[r] = p0[r] - mn; p1[r] = p1[r] - mn; }
;   PV_BLOCK(3)
; #pragma unroll
;   for (int r = 0; r < 16; ++r) p0[r] = __builtin_amdgcn_exp2f(p0[r]);
; }
	v_mfma_f32_32x32x16_bf16 v[2:17], v[194:197], v[226:229], v[2:17]
	v_mfma_f32_32x32x16_bf16 v[50:65], v[130:133], v[214:217], v[50:65]
	v_max3_f32 v144, v144, v66, v67
	v_max3_f32 v144, v144, v68, v69
	v_max3_f32 v144, v144, v70, v71
	v_max3_f32 v144, v144, v72, v73
	v_max3_f32 v144, v144, v74, v75
	v_max3_f32 v144, v144, v76, v77
	v_max3_f32 v144, v144, v78, v79
	v_mfma_f32_32x32x16_bf16 v[50:65], v[186:189], v[218:221], v[50:65]
	v_max3_f32 v144, v144, v80, v81
	v_mov_b32_e32 v157, v144
	s_nop 1
	v_permlane32_swap_b32_e32 v144, v157
	v_max_f32_e32 v157, v157, v157
	v_max_f32_e32 v144, v144, v144
	v_max_f32_e32 v144, v144, v157
	v_mfma_f32_32x32x16_bf16 v[50:65], v[190:193], v[222:225], v[50:65]
	ds_read_b64_tr_b16 v[214:215], v156 offset:0x400
	v_sub_f32_e32 v157, v144, v153
	ds_read_b64_tr_b16 v[216:217], v156 offset:0xc00
	v_cmp_ge_f32_e32 vcc, s54, v157
	ds_read_b64_tr_b16 v[218:219], v156 offset:0x1400
	s_cmp_eq_u64 vcc, exec
	v_max_f32_e32 v157, v153, v153
	ds_read_b64_tr_b16 v[220:221], v156 offset:0x1c00
	v_mfma_f32_32x32x16_bf16 v[50:65], v[194:197], v[230:233], v[50:65]
	v_max_f32_e32 v144, v157, v144
	s_cselect_b64 vcc, -1, 0
	ds_read_b64_tr_b16 v[222:223], v156 offset:0x2400
	v_cndmask_b32_e32 v144, v144, v153, vcc
	ds_read_b64_tr_b16 v[224:225], v156 offset:0x2c00
	v_sub_f32_e32 v153, v153, v144
	ds_read_b64_tr_b16 v[226:227], v156 offset:0x3400
	v_exp_f32_e32 v184, v153
	ds_read_b64_tr_b16 v[228:229], v156 offset:0x3c00
	s_waitcnt lgkmcnt(0)
	v_mfma_f32_32x32x16_bf16 v[34:49], v[130:133], v[214:217], v[34:49]
	ds_read_b64_tr_b16 v[214:215], v156 offset:0x600
	ds_read_b64_tr_b16 v[216:217], v156 offset:0xe00
	v_sub_f32_e32 v82, v82, v144
	v_sub_f32_e32 v83, v83, v144
	v_sub_f32_e32 v84, v84, v144
	v_sub_f32_e32 v85, v85, v144
	v_mfma_f32_32x32x16_bf16 v[34:49], v[186:189], v[218:221], v[34:49]
	ds_read_b64_tr_b16 v[218:219], v156 offset:0x1600
	ds_read_b64_tr_b16 v[220:221], v156 offset:0x1e00
	v_sub_f32_e32 v86, v86, v144
	v_sub_f32_e32 v87, v87, v144
	v_exp_f32_e32 v240, v82
	v_exp_f32_e32 v241, v83
	v_mfma_f32_32x32x16_bf16 v[34:49], v[190:193], v[222:225], v[34:49]
	ds_read_b64_tr_b16 v[222:223], v156 offset:0x2600
	ds_read_b64_tr_b16 v[224:225], v156 offset:0x2e00
	ds_read_b64_tr_b16 v[230:231], v156 offset:0x3600
	ds_read_b64_tr_b16 v[232:233], v156 offset:0x3e00
	v_sub_f32_e32 v88, v88, v144
	v_sub_f32_e32 v89, v89, v144
	v_exp_f32_e32 v242, v84
	v_exp_f32_e32 v243, v85
	s_waitcnt lgkmcnt(0)
	v_mfma_f32_32x32x16_bf16 v[34:49], v[194:197], v[226:229], v[34:49]
	v_sub_f32_e32 v90, v90, v144
	v_sub_f32_e32 v91, v91, v144
	v_exp_f32_e32 v244, v86
	v_exp_f32_e32 v245, v87
	v_mfma_f32_32x32x16_bf16 v[18:33], v[130:133], v[214:217], v[18:33]
	v_sub_f32_e32 v92, v92, v144
	v_sub_f32_e32 v93, v93, v144
	v_exp_f32_e32 v246, v88
	v_exp_f32_e32 v247, v89
	s_add_i32 s9, s8, 0
	v_add_u32_e32 v130, s9, v164
	s_waitcnt vmcnt(0)
	s_waitcnt vmcnt(4)
	ds_write_b128 v130, v[198:201]
	v_add_u32_e32 v130, s9, v165
	s_waitcnt vmcnt(2)
	ds_write_b128 v130, v[206:209]
	v_add_u32_e32 v130, s9, v167
	v_mfma_f32_32x32x16_bf16 v[18:33], v[186:189], v[218:221], v[18:33]
	ds_write_b128 v130, v[202:205] offset:16384
	v_add_u32_e32 v130, s9, v168
	s_waitcnt vmcnt(1)
	ds_write_b128 v130, v[210:213] offset:16384
	v_add_u32_e32 v130, s9, v169
	v_cmp_gt_f32_e32 vcc, 1.0, v184
	s_waitcnt vmcnt(0)
	ds_write_b128 v130, v[146:149] offset:32768
	v_sub_f32_e32 v94, v94, v144
	v_sub_f32_e32 v95, v95, v144
	v_exp_f32_e32 v248, v90
	v_exp_f32_e32 v249, v91
	v_mfma_f32_32x32x16_bf16 v[18:33], v[190:193], v[222:225], v[18:33]
	v_sub_f32_e32 v96, v96, v144
	v_sub_f32_e32 v97, v97, v144
	v_exp_f32_e32 v250, v92
	v_exp_f32_e32 v251, v93
	v_mfma_f32_32x32x16_bf16 v[18:33], v[194:197], v[230:233], v[18:33]
	v_exp_f32_e32 v252, v94
	v_exp_f32_e32 v253, v95
	v_exp_f32_e32 v254, v96
	v_exp_f32_e32 v255, v97
	s_cbranch_vccz .LBB0_673
	s_and_saveexec_b64 s[4:5], s[2:3]
	ds_write_b32 v161, v184 offset:128
	s_or_b64 exec, exec, s[4:5]
	s_waitcnt lgkmcnt(0)
	v_add_u32_e32 v153, v137, v134
	ds_read_b128 v[130:133], v153 offset:224
	ds_read_b128 v[146:149], v153 offset:192
	ds_read_b128 v[186:189], v153 offset:160
	ds_read_b128 v[190:193], v153 offset:128
	s_waitcnt lgkmcnt(3)
	v_pk_mul_f32 v[14:15], v[14:15], v[130:131]
	s_waitcnt lgkmcnt(2)
	v_pk_mul_f32 v[10:11], v[10:11], v[146:147]
	s_waitcnt lgkmcnt(1)
	v_pk_mul_f32 v[6:7], v[6:7], v[186:187]
	v_pk_mul_f32 v[16:17], v[16:17], v[132:133]
	v_pk_mul_f32 v[12:13], v[12:13], v[148:149]
	v_pk_mul_f32 v[8:9], v[8:9], v[188:189]
	s_waitcnt lgkmcnt(0)
	v_pk_mul_f32 v[4:5], v[4:5], v[192:193]
	v_pk_mul_f32 v[2:3], v[2:3], v[190:191]
	v_pk_mul_f32 v[62:63], v[62:63], v[130:131]
	v_pk_mul_f32 v[58:59], v[58:59], v[146:147]
	v_pk_mul_f32 v[54:55], v[54:55], v[186:187]
	v_pk_mul_f32 v[64:65], v[64:65], v[132:133]
	v_pk_mul_f32 v[60:61], v[60:61], v[148:149]
	v_pk_mul_f32 v[56:57], v[56:57], v[188:189]
	v_pk_mul_f32 v[52:53], v[52:53], v[192:193]
	v_pk_mul_f32 v[50:51], v[50:51], v[190:191]
	v_pk_mul_f32 v[46:47], v[46:47], v[130:131]
	v_pk_mul_f32 v[42:43], v[42:43], v[146:147]
	v_pk_mul_f32 v[38:39], v[38:39], v[186:187]
	v_pk_mul_f32 v[48:49], v[48:49], v[132:133]
	v_pk_mul_f32 v[44:45], v[44:45], v[148:149]
	v_pk_mul_f32 v[40:41], v[40:41], v[188:189]
	v_pk_mul_f32 v[36:37], v[36:37], v[192:193]
	v_pk_mul_f32 v[34:35], v[34:35], v[190:191]
	v_pk_mul_f32 v[30:31], v[30:31], v[130:131]
	v_pk_mul_f32 v[26:27], v[26:27], v[146:147]
	v_pk_mul_f32 v[22:23], v[22:23], v[186:187]
	v_pk_mul_f32 v[32:33], v[32:33], v[132:133]
	v_pk_mul_f32 v[28:29], v[28:29], v[148:149]
	v_pk_mul_f32 v[24:25], v[24:25], v[188:189]
	v_pk_mul_f32 v[20:21], v[20:21], v[192:193]
	v_pk_mul_f32 v[18:19], v[18:19], v[190:191]
